# diff-attention interior iterations hand-scheduled (software-pipelined units), ALiBi key term carried in QK accumulator C input (fp32)
# speedup vs baseline: 1.1170x; 1.0128x over previous
;     ...
;   const bf16x8 ones = bf16x8{0x3F80, 0x3F80, 0x3F80, 0x3F80, 0x3F80, 0x3F80, 0x3F80, 0x3F80};
;   f32x4 L[NQ * NMAP];
; #pragma unroll
;   for (int i = 0; i < NQ * NMAP; ++i) L[i] = f32x4{0.f, 0.f, 0.f, 0.f};
;   int nxt = next_tile(kt);
;   {
;     u32x4 fk[TK][2], fv[TK][2];
; #pragma unroll
;     for (int t = 0; t < TK; ++t)
; #pragma unroll
;       for (int i = 0; i < 2; ++i) {
;         fk[t][i] = *(const u32x4*)(gk + (size_t)((kt + t) * 64 + i * 32) * kstride);
;         fv[t][i] = *(const u32x4*)(gv + (size_t)(i * 32) * vtstride + (kt + t) * 64);
;       }
;     if (nxt < kt_end) gload(nxt);
;     hook();
;     __syncthreads();
; #pragma unroll
;     for (int t = 0; t < TK; ++t)
; #pragma unroll
;       for (int i = 0; i < 2; ++i) {
;         *(u32x4*)(wk + t * TSZ + i * 32 * 64) = fk[t][i];
;         *(u32x4*)(wv + t * TSZ + i * 32 * 72) = fv[t][i];
;       }
;   }
;   __syncthreads();
;   int stg = 0;
; __device__ void item_diff(const Params& p, int layer, int b, int hd, int qt, unsigned char* smem) {
;     ...
;   const float slope2 = exp2f(-2.f * (float)(hd + 1)) * LOG2E;
;   const unsigned selq[1] = {0xffffffffu};
;   const float c1 = 0.17677669529663687f * LOG2E;
.LBB0_202:
	s_mov_b64 s[30:31], 0x20000
	v_lshlrev_b32_e32 v80, 7, v2
	v_lshlrev_b32_e32 v2, 4, v2
	v_lshl_add_u64 v[134:135], v[132:133], 0, s[30:31]
	s_not_b32 s30, s38
	v_lshrrev_b32_e32 v78, 4, v77
	v_bfe_u32 v79, v77, 4, 2
	v_add3_u32 v146, v80, v2, v0
	v_bfe_u32 v0, v77, 1, 3
	s_lshl_b32 s30, s30, 1
	v_lshlrev_b32_e32 v147, 2, v79
	v_bitop3_b32 v2, v78, v0, 3 bitop3:0x6c
	v_bitop3_b32 v0, v79, v0, 4 bitop3:0x36
	v_ldexp_f32 v3, 1.0, s30
	v_xor_b32_e32 v81, v78, v77
	v_lshlrev_b32_e32 v151, 4, v0
	s_lshl_b32 s29, s29, 6
	v_sub_u32_e32 v0, v76, v147
	v_mul_f32_e32 v129, 0x3fb8aa3b, v3
	v_and_b32_e32 v3, 15, v77
	v_lshlrev_b32_e32 v81, 4, v81
	s_movk_i32 s30, 0x70
	v_subrev_u32_e32 v152, s29, v0
	v_or_b32_e32 v0, s29, v147
	v_and_or_b32 v145, v81, s30, v80
	v_lshlrev_b32_e32 v148, 7, v3
	v_mul_u32_u24_e32 v149, 0x90, v3
	v_lshlrev_b32_e32 v150, 4, v2
	v_sub_u32_e32 v0, v0, v76
	v_mov_b32_e32 v2, v1
	v_mov_b32_e32 v3, v1
	s_waitcnt lgkmcnt(0)
	s_barrier
	s_waitcnt vmcnt(7)
	ds_write_b128 v145, v[28:31]
	s_waitcnt vmcnt(6)
	ds_write_b128 v146, v[36:39] offset:9216
	s_waitcnt vmcnt(5)
	ds_write_b128 v145, v[40:43] offset:4096
	s_waitcnt vmcnt(1)
	ds_write_b128 v146, v[72:75] offset:13824
	ds_write_b128 v145, v[60:63] offset:18432
	ds_write_b128 v146, v[48:51] offset:27648
	ds_write_b128 v145, v[64:67] offset:22528
	s_waitcnt vmcnt(0)
	ds_write_b128 v146, v[68:71] offset:32256
	v_subrev_u32_e32 v153, s35, v0
	v_mov_b32_e32 v0, v1
	v_mov_b64_e32 v[66:67], v[2:3]
	v_mov_b64_e32 v[74:75], v[2:3]
	v_mov_b64_e32 v[78:79], v[2:3]
	v_mov_b64_e32 v[82:83], v[2:3]
	v_mov_b64_e32 v[62:63], v[2:3]
	v_mov_b64_e32 v[50:51], v[2:3]
	v_mov_b64_e32 v[38:39], v[2:3]
	v_mov_b64_e32 v[30:31], v[2:3]
	v_mov_b64_e32 v[70:71], v[2:3]
	v_mov_b64_e32 v[42:43], v[2:3]
	s_or_b32 s77, s74, 15
	s_mov_b32 s78, 4
	s_add_i32 s79, s29, 0x7ffff830
	s_mov_b32 s80, 0
	v_mov_b64_e32 v[64:65], v[0:1]
	v_mov_b64_e32 v[72:73], v[0:1]
	v_mov_b64_e32 v[76:77], v[0:1]
	v_mov_b64_e32 v[80:81], v[0:1]
	v_mov_b64_e32 v[60:61], v[0:1]
	v_mov_b64_e32 v[48:49], v[0:1]
	v_mov_b64_e32 v[36:37], v[0:1]
	v_mov_b64_e32 v[28:29], v[0:1]
	v_mov_b64_e32 v[68:69], v[0:1]
	v_mov_b64_e32 v[40:41], v[0:1]
	s_mov_b32 s81, 0
	s_waitcnt lgkmcnt(0)
	s_barrier
	v_mul_f32_e32 v230, 0x407af232, v129
	v_mul_f32_e32 v231, 0x3f800000, v230
	v_mul_f32_e32 v232, 0x40000000, v230
	v_mul_f32_e32 v233, 0x40400000, v230
	v_mul_f32_e32 v234, 0x41800000, v230
	v_mul_f32_e32 v235, 0x41880000, v230
	v_mul_f32_e32 v236, 0x41900000, v230
	v_mul_f32_e32 v237, 0x41980000, v230
	v_mul_f32_e32 v242, 0x42000000, v230
	v_mul_f32_e32 v243, 0x42040000, v230
	v_mul_f32_e32 v244, 0x42080000, v230
	v_mul_f32_e32 v245, 0x420c0000, v230
	v_mul_f32_e32 v246, 0x42400000, v230
	v_mul_f32_e32 v247, 0x42440000, v230
	v_mul_f32_e32 v248, 0x42480000, v230
	v_mul_f32_e32 v249, 0x424c0000, v230
	v_mov_b32_e32 v230, 0
	s_branch .LBB0_205

;     ...
;   while (kt < kt_end) {
;     const int nxt2 = (nxt < kt_end) ? next_tile(nxt) : kt_end;
;     if (nxt < kt_end) lstore(stg ^ 1);
;     if (nxt2 < kt_end) gload(nxt2);
; #pragma unroll
;     for (int hk = 0; hk < TK; ++hk) {
;     const u16* cK = sK + stg * FST + hk * TSZ;
;     const u16* cV = cK + 64 * 72;
;     const int k0 = (kt + hk) * 64;
;     if (k0 <= qhi && (qlo - (k0 + 63)) < window) {
;       bool full = (k0 + 63 <= qlo) && (qhi - k0 < window);
.LBB0_205:
	s_add_i32 s82, s78, -2
	s_cmp_gt_i32 s82, s75
	s_cbranch_scc1 .Ldf_slow
	s_add_i32 s29, s80, 0x7f
	s_cmp_gt_i32 s29, s74
	s_cbranch_scc1 .Ldf_slow
	s_cmp_eq_u32 s35, s79
	s_cbranch_scc0 .Ldf_iter
.Ldf_slow:
	s_cmp_gt_i32 s82, s75
	s_cselect_b64 s[30:31], -1, 0
	s_and_b64 vcc, exec, s[30:31]
	s_cbranch_vccnz .LBB0_207
	s_xor_b32 s29, s81, 1
	s_mul_i32 s29, s29, 0x9000
	v_add_u32_e32 v0, s29, v145
	v_add_u32_e32 v2, s29, v146
	s_waitcnt vmcnt(7)
	ds_write_b128 v0, v[12:15]
	s_waitcnt vmcnt(6)
	ds_write_b128 v2, v[20:23] offset:9216
	s_waitcnt vmcnt(5)
	ds_write_b128 v0, v[16:19] offset:4096
	s_waitcnt vmcnt(4)
	ds_write_b128 v2, v[24:27] offset:13824
	s_waitcnt vmcnt(3)
	ds_write_b128 v0, v[44:47] offset:18432
	s_waitcnt vmcnt(2)
	ds_write_b128 v2, v[32:35] offset:27648
	s_waitcnt vmcnt(1)
	ds_write_b128 v0, v[56:59] offset:22528
	s_waitcnt vmcnt(0)
	ds_write_b128 v2, v[52:55] offset:32256

;     ...
;   while (kt < kt_end) {
;     const int nxt2 = (nxt < kt_end) ? next_tile(nxt) : kt_end;
;     if (nxt < kt_end) lstore(stg ^ 1);
;     if (nxt2 < kt_end) gload(nxt2);
; #pragma unroll
;     for (int hk = 0; hk < TK; ++hk) {
;     const u16* cK = sK + stg * FST + hk * TSZ;
;     const u16* cV = cK + 64 * 72;
;     const int k0 = (kt + hk) * 64;
;     if (k0 <= qhi && (qlo - (k0 + 63)) < window) {
;       bool full = (k0 + 63 <= qlo) && (qhi - k0 < window);
;       const bool rowfull = SEL && full;
;       bool selok[NQ];
; #pragma unroll
;       for (int n = 0; n < NQ; ++n) selok[n] = true;
;       if (SEL) {
;         bool all = true;
; #pragma unroll
;         for (int n = 0; n < NQ; ++n) { selok[n] = ((selq[n] >> kt) & 1u) != 0; all = all && selok[n]; }
;         full = full && __all(all);
;       }
;       const int kbase = k0 + quad * 4;
; #pragma unroll
;       for (int mp = 0; mp < NMAP; ++mp) {
; #pragma unroll
;         for (int n = 0; n < NQ; ++n) {
;           f32x4 S[4];
; #pragma unroll
;           for (int mt = 0; mt < 4; ++mt) S[mt] = f32x4{0.f, 0.f, 0.f, 0.f};
; #pragma unroll
;           for (int ks = 0; ks < 2; ++ks) {
;             if (NMAP == 2 && ks != mp) continue;
; #pragma unroll
;             for (int mt = 0; mt < 4; ++mt) {
;               bf16x8 a = *(const bf16x8*)(cK + (mt * 16 + l15) * 64 + (((ks * 4 + quad) ^ ((l15 >> 1) & 7)) * 8));
;               S[mt] = mfma16(a, qf[n][ks], S[mt]);
;             }
;           }
;           bf16x8 pb[2];
;           const float tb = slope2 * (float)(kbase - tq[n]);
;           if (full || rowfull) {
;             sm_step<false>(S, c1, slope2, tb, kbase, tq[n], window, true, pb);
;             if (SEL && !full && !selok[n]) {
;               pb[0] = bf16x8{0, 0, 0, 0, 0, 0, 0, 0}; pb[1] = bf16x8{0, 0, 0, 0, 0, 0, 0, 0};
;             }
;           } else sm_step<true>(S, c1, slope2, tb, kbase, tq[n], window, selok[n], pb);
; #pragma unroll
;           for (int k2 = 0; k2 < 2; ++k2) {
; #pragma unroll
;             for (int dt = 0; dt < 4; ++dt) {
;               bf16x8 a = vt_frag(cV, dt, k2, l15, quad);
;               O[mp * NQ + n][dt] = mfma16(a, pb[k2], O[mp * NQ + n][dt]);
;             }
;             L[mp * NQ + n] = mfma16(ones, pb[k2], L[mp * NQ + n]);
;           }
.Ldf_iter:
	s_mul_i32 s83, s81, 0x9000
	s_xor_b32 s29, s81, 1
	s_mul_i32 s29, s29, 0x9000
	v_add_u32_e32 v0, s83, v148
	v_add_u32_e32 v156, v0, v150
	v_add_u32_e32 v157, v0, v151
	ds_read_b128 v[174:177], v156
	ds_read_b128 v[178:181], v156 offset:2048
	ds_read_b128 v[116:119], v156 offset:4096
	ds_read_b128 v[206:209], v156 offset:6144
	v_add_u32_e32 v0, s29, v145
	v_add_u32_e32 v2, s29, v146
	s_waitcnt vmcnt(7)
	ds_write_b128 v0, v[12:15]
	s_waitcnt vmcnt(6)
	ds_write_b128 v2, v[20:23] offset:9216
	s_waitcnt vmcnt(5)
	ds_write_b128 v0, v[16:19] offset:4096
	s_waitcnt vmcnt(4)
	ds_write_b128 v2, v[24:27] offset:13824
	s_waitcnt vmcnt(3)
	ds_write_b128 v0, v[44:47] offset:18432
	s_waitcnt vmcnt(2)
	ds_write_b128 v2, v[32:35] offset:27648
	s_waitcnt vmcnt(1)
	ds_write_b128 v0, v[56:59] offset:22528
	s_waitcnt vmcnt(0)
	ds_write_b128 v2, v[52:55] offset:32256
	s_cmp_gt_i32 s78, s75
	s_cbranch_scc1 .Ldf_nogl
	s_lshl_b32 s86, s78, 6
	v_mad_u64_u32 v[2:3], s[30:31], s86, v228, v[130:131]
	s_lshl_b64 s[30:31], s[86:87], 1
	s_or_b32 s29, s86, 32
	v_lshl_add_u64 v[16:17], v[132:133], 0, s[30:31]
	global_load_dwordx4 v[12:15], v[2:3], off offset:512
	global_load_dwordx4 v[20:23], v[16:17], off
	v_mad_u64_u32 v[2:3], s[38:39], s29, v228, v[130:131]
	v_lshl_add_u64 v[24:25], v[134:135], 0, s[30:31]
	s_or_b32 s30, s86, 64
	global_load_dwordx4 v[16:19], v[2:3], off offset:512
	s_nop 0
	global_load_dwordx4 v[24:27], v[24:25], off
	v_mad_i64_i32 v[2:3], s[38:39], s30, v228, v[130:131]
	s_ashr_i32 s39, s86, 31
	s_mov_b32 s38, s86
	s_ashr_i32 s31, s30, 31
	v_lshl_add_u64 v[32:33], s[38:39], 1, v[132:133]
	s_or_b32 s29, s86, 0x60
	global_load_dwordx4 v[44:47], v[2:3], off offset:512
	s_nop 0
	global_load_dwordx4 v[32:35], v[32:33], off offset:128
	v_mad_i64_i32 v[2:3], s[38:39], s29, v228, v[130:131]
	v_lshl_add_u64 v[52:53], s[30:31], 1, v[134:135]
	global_load_dwordx4 v[56:59], v[2:3], off offset:512
	s_nop 0
	global_load_dwordx4 v[52:55], v[52:53], off
.Ldf_nogl:
	v_lshlrev_b32_e32 v0, 1, v147
	v_add3_u32 v0, s83, v0, v149
	v_add_u32_e32 v238, 0x2000, v0
	v_add_u32_e32 v239, 0x2800, v0
	v_add_u32_e32 v240, 0x3000, v0
	v_add_u32_e32 v241, 0x3800, v0
	v_add_u32_e32 v2, s80, v153
	v_add_u32_e32 v3, 0xfffff840, v2
	v_cvt_f32_i32_e32 v3, v3
	v_mul_f32_e32 v154, v129, v3
	v_add_u32_e32 v3, 0xfffff880, v2
	v_cvt_f32_i32_e32 v3, v3
	v_mul_f32_e32 v155, v129, v3
	s_mov_b32 s29, s28
	s_mov_b32 s30, s28
	s_mov_b32 s31, s28
	v_mov_b64_e32 v[136:137], s[28:29]
	v_mov_b64_e32 v[138:139], s[30:31]
	s_waitcnt lgkmcnt(11)
	v_mfma_f32_16x16x32_bf16 v[158:161], v[174:177], v[4:7], v[230:233]
	s_waitcnt lgkmcnt(10)
	v_mfma_f32_16x16x32_bf16 v[162:165], v[178:181], v[4:7], v[234:237]
	s_waitcnt lgkmcnt(9)
	v_mfma_f32_16x16x32_bf16 v[166:169], v[116:119], v[4:7], v[242:245]
	s_waitcnt lgkmcnt(8)
	v_mfma_f32_16x16x32_bf16 v[170:173], v[206:209], v[4:7], v[246:249]
	ds_read_b128 v[174:177], v157
	ds_read_b128 v[178:181], v157 offset:2048
	ds_read_b128 v[116:119], v157 offset:4096
	ds_read_b128 v[206:209], v157 offset:6144
	ds_read2_b64 v[84:87], v238 offset0:128 offset1:132
	ds_read2_b64 v[88:91], v239 offset0:160 offset1:164
	ds_read2_b64 v[92:95], v240 offset0:192 offset1:196
	ds_read2_b64 v[96:99], v241 offset0:224 offset1:228
	ds_read2_b64 v[100:103], v238 offset0:136 offset1:140
	ds_read2_b64 v[104:107], v239 offset0:168 offset1:172
	ds_read2_b64 v[108:111], v240 offset0:200 offset1:204
	ds_read2_b64 v[112:115], v241 offset0:232 offset1:236
	v_fmamk_f32 v158, v158, 0x3e8293ee, v154
	v_fmamk_f32 v159, v159, 0x3e8293ee, v154
	v_fmamk_f32 v160, v160, 0x3e8293ee, v154
	v_fmamk_f32 v161, v161, 0x3e8293ee, v154
	v_fmamk_f32 v162, v162, 0x3e8293ee, v154
	v_fmamk_f32 v163, v163, 0x3e8293ee, v154
	v_fmamk_f32 v164, v164, 0x3e8293ee, v154
	v_fmamk_f32 v165, v165, 0x3e8293ee, v154
	v_exp_f32_e32 v158, v158
	v_exp_f32_e32 v159, v159
	v_exp_f32_e32 v160, v160
	v_exp_f32_e32 v161, v161
	v_fmamk_f32 v166, v166, 0x3e8293ee, v154
	v_fmamk_f32 v167, v167, 0x3e8293ee, v154
	v_fmamk_f32 v168, v168, 0x3e8293ee, v154
	v_fmamk_f32 v169, v169, 0x3e8293ee, v154
	v_exp_f32_e32 v162, v162
	v_exp_f32_e32 v163, v163
	v_exp_f32_e32 v164, v164
	v_exp_f32_e32 v165, v165
	v_cvt_pk_bf16_f32 v198, v158, v159
	v_cvt_pk_bf16_f32 v199, v160, v161
	v_fmamk_f32 v170, v170, 0x3e8293ee, v154
	v_fmamk_f32 v171, v171, 0x3e8293ee, v154
	v_fmamk_f32 v172, v172, 0x3e8293ee, v154
	v_fmamk_f32 v173, v173, 0x3e8293ee, v154
	s_waitcnt lgkmcnt(11)
	v_mfma_f32_16x16x32_bf16 v[182:185], v[174:177], v[8:11], v[230:233]
	v_exp_f32_e32 v166, v166
	v_exp_f32_e32 v167, v167
	v_exp_f32_e32 v168, v168
	s_waitcnt lgkmcnt(10)
	v_mfma_f32_16x16x32_bf16 v[186:189], v[178:181], v[8:11], v[234:237]
	v_exp_f32_e32 v169, v169
	v_cvt_pk_bf16_f32 v200, v162, v163
	v_cvt_pk_bf16_f32 v201, v164, v165
	v_exp_f32_e32 v170, v170
	s_waitcnt lgkmcnt(9)
	v_mfma_f32_16x16x32_bf16 v[190:193], v[116:119], v[8:11], v[242:245]
	v_exp_f32_e32 v171, v171
	v_exp_f32_e32 v172, v172
	v_exp_f32_e32 v173, v173
	s_waitcnt lgkmcnt(8)
	v_mfma_f32_16x16x32_bf16 v[194:197], v[206:209], v[8:11], v[246:249]
	ds_read_b128 v[174:177], v156 offset:18432
	ds_read_b128 v[178:181], v156 offset:20480
	ds_read_b128 v[116:119], v156 offset:22528
	ds_read_b128 v[206:209], v156 offset:24576
	v_cvt_pk_bf16_f32 v202, v166, v167
	v_cvt_pk_bf16_f32 v203, v168, v169
	v_cvt_pk_bf16_f32 v204, v170, v171
	v_cvt_pk_bf16_f32 v205, v172, v173
	v_fmamk_f32 v182, v182, 0x3e8293ee, v154
	v_fmamk_f32 v183, v183, 0x3e8293ee, v154
	v_fmamk_f32 v184, v184, 0x3e8293ee, v154
	v_fmamk_f32 v185, v185, 0x3e8293ee, v154
	s_waitcnt lgkmcnt(11)
; __device__ __forceinline__ float fexp2(float x) { return __builtin_amdgcn_exp2f(x); }
; template <bool MASKED>
; __device__ __forceinline__ void sm_step(f32x4 (&S)[4], float c1, float slope2, float tb, int kbase, int tqn,
;                                         int window, bool selok, bf16x8 (&pb)[2]) {
; #pragma unroll
;   for (int mt = 0; mt < 4; ++mt)
; #pragma unroll
;     for (int r = 0; r < 4; ++r) {
;       float u = fmaf(slope2, (float)(mt * 16 + r), fmaf(S[mt][r], c1, tb));
;       if (MASKED) {
;         int dist = tqn - (kbase + mt * 16 + r);
;         bool valid = (dist >= 0) && (dist < window) && selok;
;         u = valid ? u : -1e30f;
;       }
;       S[mt][r] = fexp2(u);
;     }
; #pragma unroll
;   for (int k2 = 0; k2 < 2; ++k2)
;     pb[k2] = pack8(S[2 * k2][0], S[2 * k2][1], S[2 * k2][2], S[2 * k2][3],
;                    S[2 * k2 + 1][0], S[2 * k2 + 1][1], S[2 * k2 + 1][2], S[2 * k2 + 1][3]);
; }
;     ...
; #pragma unroll
;       for (int mp = 0; mp < NMAP; ++mp) {
; #pragma unroll
;         for (int n = 0; n < NQ; ++n) {
;           f32x4 S[4];
; #pragma unroll
;           for (int mt = 0; mt < 4; ++mt) S[mt] = f32x4{0.f, 0.f, 0.f, 0.f};
; #pragma unroll
;           for (int ks = 0; ks < 2; ++ks) {
;             if (NMAP == 2 && ks != mp) continue;
; #pragma unroll
;             for (int mt = 0; mt < 4; ++mt) {
;               bf16x8 a = *(const bf16x8*)(cK + (mt * 16 + l15) * 64 + (((ks * 4 + quad) ^ ((l15 >> 1) & 7)) * 8));
;               S[mt] = mfma16(a, qf[n][ks], S[mt]);
;             }
;           }
;           bf16x8 pb[2];
;           const float tb = slope2 * (float)(kbase - tq[n]);
;           if (full || rowfull) {
;             sm_step<false>(S, c1, slope2, tb, kbase, tq[n], window, true, pb);
;             if (SEL && !full && !selok[n]) {
;               pb[0] = bf16x8{0, 0, 0, 0, 0, 0, 0, 0}; pb[1] = bf16x8{0, 0, 0, 0, 0, 0, 0, 0};
;             }
;           } else sm_step<true>(S, c1, slope2, tb, kbase, tq[n], window, selok[n], pb);
; #pragma unroll
;           for (int k2 = 0; k2 < 2; ++k2) {
; #pragma unroll
;             for (int dt = 0; dt < 4; ++dt) {
;               bf16x8 a = vt_frag(cV, dt, k2, l15, quad);
;               O[mp * NQ + n][dt] = mfma16(a, pb[k2], O[mp * NQ + n][dt]);
;             }
;             L[mp * NQ + n] = mfma16(ones, pb[k2], L[mp * NQ + n]);
;           }
	v_mfma_f32_16x16x32_bf16 v[80:83], v[84:87], v[198:201], v[80:83]
	v_fmamk_f32 v186, v186, 0x3e8293ee, v154
	v_fmamk_f32 v187, v187, 0x3e8293ee, v154
	v_fmamk_f32 v188, v188, 0x3e8293ee, v154
	v_fmamk_f32 v189, v189, 0x3e8293ee, v154
	s_waitcnt lgkmcnt(10)
	v_mfma_f32_16x16x32_bf16 v[76:79], v[88:91], v[198:201], v[76:79]
	v_exp_f32_e32 v182, v182
	v_exp_f32_e32 v183, v183
	s_waitcnt lgkmcnt(9)
	v_mfma_f32_16x16x32_bf16 v[72:75], v[92:95], v[198:201], v[72:75]
	v_exp_f32_e32 v184, v184
	v_exp_f32_e32 v185, v185
	s_waitcnt lgkmcnt(8)
	v_mfma_f32_16x16x32_bf16 v[64:67], v[96:99], v[198:201], v[64:67]
	v_fmamk_f32 v190, v190, 0x3e8293ee, v154
	v_fmamk_f32 v191, v191, 0x3e8293ee, v154
	v_fmamk_f32 v192, v192, 0x3e8293ee, v154
	v_mfma_f32_16x16x32_bf16 v[68:71], v[136:139], v[198:201], v[68:71]
	v_fmamk_f32 v193, v193, 0x3e8293ee, v154
	v_exp_f32_e32 v186, v186
	v_exp_f32_e32 v187, v187
	s_waitcnt lgkmcnt(7)
	v_mfma_f32_16x16x32_bf16 v[80:83], v[100:103], v[202:205], v[80:83]
	v_exp_f32_e32 v188, v188
	v_exp_f32_e32 v189, v189
	s_waitcnt lgkmcnt(6)
	v_mfma_f32_16x16x32_bf16 v[76:79], v[104:107], v[202:205], v[76:79]
	v_cvt_pk_bf16_f32 v218, v182, v183
	v_cvt_pk_bf16_f32 v219, v184, v185
	s_waitcnt lgkmcnt(5)
	v_mfma_f32_16x16x32_bf16 v[72:75], v[108:111], v[202:205], v[72:75]
	v_fmamk_f32 v194, v194, 0x3e8293ee, v154
	v_fmamk_f32 v195, v195, 0x3e8293ee, v154
	v_fmamk_f32 v196, v196, 0x3e8293ee, v154
	v_fmamk_f32 v197, v197, 0x3e8293ee, v154
	s_waitcnt lgkmcnt(4)
	v_mfma_f32_16x16x32_bf16 v[64:67], v[112:115], v[202:205], v[64:67]
	v_exp_f32_e32 v190, v190
	v_exp_f32_e32 v191, v191
	v_mfma_f32_16x16x32_bf16 v[68:71], v[136:139], v[202:205], v[68:71]
	v_exp_f32_e32 v192, v192
	v_exp_f32_e32 v193, v193
	v_cvt_pk_bf16_f32 v220, v186, v187
	s_waitcnt lgkmcnt(3)
	v_mfma_f32_16x16x32_bf16 v[158:161], v[174:177], v[4:7], v[230:233]
	v_cvt_pk_bf16_f32 v221, v188, v189
	v_exp_f32_e32 v194, v194
	s_waitcnt lgkmcnt(2)
	v_mfma_f32_16x16x32_bf16 v[162:165], v[178:181], v[4:7], v[234:237]
	v_exp_f32_e32 v195, v195
	v_exp_f32_e32 v196, v196
	s_waitcnt lgkmcnt(1)
	v_mfma_f32_16x16x32_bf16 v[166:169], v[116:119], v[4:7], v[242:245]
	v_exp_f32_e32 v197, v197
	v_cvt_pk_bf16_f32 v222, v190, v191
	s_waitcnt lgkmcnt(0)
	v_mfma_f32_16x16x32_bf16 v[170:173], v[206:209], v[4:7], v[246:249]
	ds_read_b128 v[174:177], v157 offset:18432
	ds_read_b128 v[178:181], v157 offset:20480
	ds_read_b128 v[116:119], v157 offset:22528
	ds_read_b128 v[206:209], v157 offset:24576
	v_cvt_pk_bf16_f32 v223, v192, v193
	v_cvt_pk_bf16_f32 v224, v194, v195
	v_cvt_pk_bf16_f32 v225, v196, v197
	v_fmamk_f32 v158, v158, 0x3e8293ee, v155
	v_fmamk_f32 v159, v159, 0x3e8293ee, v155
	v_fmamk_f32 v160, v160, 0x3e8293ee, v155
	v_fmamk_f32 v161, v161, 0x3e8293ee, v155
	v_mfma_f32_16x16x32_bf16 v[60:63], v[84:87], v[218:221], v[60:63]
	v_fmamk_f32 v162, v162, 0x3e8293ee, v155
	v_fmamk_f32 v163, v163, 0x3e8293ee, v155
	v_fmamk_f32 v164, v164, 0x3e8293ee, v155
	v_fmamk_f32 v165, v165, 0x3e8293ee, v155
	v_mfma_f32_16x16x32_bf16 v[48:51], v[88:91], v[218:221], v[48:51]
	v_exp_f32_e32 v158, v158
	v_exp_f32_e32 v159, v159
	v_mfma_f32_16x16x32_bf16 v[36:39], v[92:95], v[218:221], v[36:39]
	v_exp_f32_e32 v160, v160
	v_exp_f32_e32 v161, v161
	v_mfma_f32_16x16x32_bf16 v[28:31], v[96:99], v[218:221], v[28:31]
	v_fmamk_f32 v166, v166, 0x3e8293ee, v155
	v_fmamk_f32 v167, v167, 0x3e8293ee, v155
	v_fmamk_f32 v168, v168, 0x3e8293ee, v155
	v_mfma_f32_16x16x32_bf16 v[40:43], v[136:139], v[218:221], v[40:43]
	v_add_u32_e32 v238, 0x4800, v238
	v_add_u32_e32 v239, 0x4800, v239
	v_add_u32_e32 v240, 0x4800, v240
	v_add_u32_e32 v241, 0x4800, v241
	ds_read2_b64 v[84:87], v238 offset0:128 offset1:132
	ds_read2_b64 v[88:91], v239 offset0:160 offset1:164
	ds_read2_b64 v[92:95], v240 offset0:192 offset1:196
	ds_read2_b64 v[96:99], v241 offset0:224 offset1:228
	v_fmamk_f32 v169, v169, 0x3e8293ee, v155
	v_exp_f32_e32 v162, v162
	v_exp_f32_e32 v163, v163
	v_mfma_f32_16x16x32_bf16 v[60:63], v[100:103], v[222:225], v[60:63]
	v_exp_f32_e32 v164, v164
	v_exp_f32_e32 v165, v165
	v_mfma_f32_16x16x32_bf16 v[48:51], v[104:107], v[222:225], v[48:51]
	v_cvt_pk_bf16_f32 v198, v158, v159
	v_cvt_pk_bf16_f32 v199, v160, v161
	v_mfma_f32_16x16x32_bf16 v[36:39], v[108:111], v[222:225], v[36:39]
	v_fmamk_f32 v170, v170, 0x3e8293ee, v155
	v_fmamk_f32 v171, v171, 0x3e8293ee, v155
	v_fmamk_f32 v172, v172, 0x3e8293ee, v155
	v_fmamk_f32 v173, v173, 0x3e8293ee, v155
	v_mfma_f32_16x16x32_bf16 v[28:31], v[112:115], v[222:225], v[28:31]
	v_exp_f32_e32 v166, v166
	v_exp_f32_e32 v167, v167
	v_mfma_f32_16x16x32_bf16 v[40:43], v[136:139], v[222:225], v[40:43]
	ds_read2_b64 v[100:103], v238 offset0:136 offset1:140
	ds_read2_b64 v[104:107], v239 offset0:168 offset1:172
	ds_read2_b64 v[108:111], v240 offset0:200 offset1:204
	ds_read2_b64 v[112:115], v241 offset0:232 offset1:236
	v_exp_f32_e32 v168, v168
	v_exp_f32_e32 v169, v169
	v_cvt_pk_bf16_f32 v200, v162, v163
	s_waitcnt lgkmcnt(11)
;     ...
; #pragma unroll
;       for (int mp = 0; mp < NMAP; ++mp) {
; #pragma unroll
;         for (int n = 0; n < NQ; ++n) {
;           f32x4 S[4];
; #pragma unroll
;           for (int mt = 0; mt < 4; ++mt) S[mt] = f32x4{0.f, 0.f, 0.f, 0.f};
; #pragma unroll
;           for (int ks = 0; ks < 2; ++ks) {
;             if (NMAP == 2 && ks != mp) continue;
; #pragma unroll
;             for (int mt = 0; mt < 4; ++mt) {
;               bf16x8 a = *(const bf16x8*)(cK + (mt * 16 + l15) * 64 + (((ks * 4 + quad) ^ ((l15 >> 1) & 7)) * 8));
;               S[mt] = mfma16(a, qf[n][ks], S[mt]);
;             }
;           }
;           bf16x8 pb[2];
;           const float tb = slope2 * (float)(kbase - tq[n]);
;           if (full || rowfull) {
;             sm_step<false>(S, c1, slope2, tb, kbase, tq[n], window, true, pb);
;             if (SEL && !full && !selok[n]) {
;               pb[0] = bf16x8{0, 0, 0, 0, 0, 0, 0, 0}; pb[1] = bf16x8{0, 0, 0, 0, 0, 0, 0, 0};
;             }
;           } else sm_step<true>(S, c1, slope2, tb, kbase, tq[n], window, selok[n], pb);
; #pragma unroll
;           for (int k2 = 0; k2 < 2; ++k2) {
; #pragma unroll
;             for (int dt = 0; dt < 4; ++dt) {
;               bf16x8 a = vt_frag(cV, dt, k2, l15, quad);
;               O[mp * NQ + n][dt] = mfma16(a, pb[k2], O[mp * NQ + n][dt]);
;             }
;             L[mp * NQ + n] = mfma16(ones, pb[k2], L[mp * NQ + n]);
;           }
;         }
;       }
;     }
;     }
;     __syncthreads();
;     kt = nxt; nxt = nxt2; stg ^= 1;
	v_mfma_f32_16x16x32_bf16 v[182:185], v[174:177], v[8:11], v[230:233]
	v_cvt_pk_bf16_f32 v201, v164, v165
	v_exp_f32_e32 v170, v170
	s_waitcnt lgkmcnt(10)
	v_mfma_f32_16x16x32_bf16 v[186:189], v[178:181], v[8:11], v[234:237]
	v_exp_f32_e32 v171, v171
	v_exp_f32_e32 v172, v172
	s_waitcnt lgkmcnt(9)
	v_mfma_f32_16x16x32_bf16 v[190:193], v[116:119], v[8:11], v[242:245]
	v_exp_f32_e32 v173, v173
	v_cvt_pk_bf16_f32 v202, v166, v167
	s_waitcnt lgkmcnt(8)
	v_mfma_f32_16x16x32_bf16 v[194:197], v[206:209], v[8:11], v[246:249]
	v_cvt_pk_bf16_f32 v203, v168, v169
	v_cvt_pk_bf16_f32 v204, v170, v171
	v_cvt_pk_bf16_f32 v205, v172, v173
	v_fmamk_f32 v182, v182, 0x3e8293ee, v155
	v_fmamk_f32 v183, v183, 0x3e8293ee, v155
	v_fmamk_f32 v184, v184, 0x3e8293ee, v155
	v_fmamk_f32 v185, v185, 0x3e8293ee, v155
	v_fmamk_f32 v186, v186, 0x3e8293ee, v155
	v_fmamk_f32 v187, v187, 0x3e8293ee, v155
	v_fmamk_f32 v188, v188, 0x3e8293ee, v155
	v_fmamk_f32 v189, v189, 0x3e8293ee, v155
	v_exp_f32_e32 v182, v182
	s_waitcnt lgkmcnt(7)
	v_mfma_f32_16x16x32_bf16 v[80:83], v[84:87], v[198:201], v[80:83]
	v_exp_f32_e32 v183, v183
	v_exp_f32_e32 v184, v184
	s_waitcnt lgkmcnt(6)
	v_mfma_f32_16x16x32_bf16 v[76:79], v[88:91], v[198:201], v[76:79]
	v_exp_f32_e32 v185, v185
	v_fmamk_f32 v190, v190, 0x3e8293ee, v155
	v_fmamk_f32 v191, v191, 0x3e8293ee, v155
	v_fmamk_f32 v192, v192, 0x3e8293ee, v155
	s_waitcnt lgkmcnt(5)
	v_mfma_f32_16x16x32_bf16 v[72:75], v[92:95], v[198:201], v[72:75]
	v_fmamk_f32 v193, v193, 0x3e8293ee, v155
	v_exp_f32_e32 v186, v186
	v_exp_f32_e32 v187, v187
	s_waitcnt lgkmcnt(4)
	v_mfma_f32_16x16x32_bf16 v[64:67], v[96:99], v[198:201], v[64:67]
	v_exp_f32_e32 v188, v188
	v_exp_f32_e32 v189, v189
	v_cvt_pk_bf16_f32 v218, v182, v183
	v_mfma_f32_16x16x32_bf16 v[68:71], v[136:139], v[198:201], v[68:71]
	v_cvt_pk_bf16_f32 v219, v184, v185
	v_fmamk_f32 v194, v194, 0x3e8293ee, v155
	v_fmamk_f32 v195, v195, 0x3e8293ee, v155
	v_fmamk_f32 v196, v196, 0x3e8293ee, v155
	s_waitcnt lgkmcnt(3)
	v_mfma_f32_16x16x32_bf16 v[80:83], v[100:103], v[202:205], v[80:83]
	v_fmamk_f32 v197, v197, 0x3e8293ee, v155
	v_exp_f32_e32 v190, v190
	v_exp_f32_e32 v191, v191
	s_waitcnt lgkmcnt(2)
	v_mfma_f32_16x16x32_bf16 v[76:79], v[104:107], v[202:205], v[76:79]
	v_exp_f32_e32 v192, v192
	v_exp_f32_e32 v193, v193
	v_cvt_pk_bf16_f32 v220, v186, v187
	s_waitcnt lgkmcnt(1)
	v_mfma_f32_16x16x32_bf16 v[72:75], v[108:111], v[202:205], v[72:75]
	v_cvt_pk_bf16_f32 v221, v188, v189
	v_exp_f32_e32 v194, v194
	v_exp_f32_e32 v195, v195
	s_waitcnt lgkmcnt(0)
	v_mfma_f32_16x16x32_bf16 v[64:67], v[112:115], v[202:205], v[64:67]
	v_exp_f32_e32 v196, v196
	v_exp_f32_e32 v197, v197
	v_mfma_f32_16x16x32_bf16 v[68:71], v[136:139], v[202:205], v[68:71]
	v_cvt_pk_bf16_f32 v222, v190, v191
	v_cvt_pk_bf16_f32 v223, v192, v193
	v_cvt_pk_bf16_f32 v224, v194, v195
	v_cvt_pk_bf16_f32 v225, v196, v197
	v_mfma_f32_16x16x32_bf16 v[60:63], v[84:87], v[218:221], v[60:63]
	v_mfma_f32_16x16x32_bf16 v[48:51], v[88:91], v[218:221], v[48:51]
	v_mfma_f32_16x16x32_bf16 v[36:39], v[92:95], v[218:221], v[36:39]
	v_mfma_f32_16x16x32_bf16 v[28:31], v[96:99], v[218:221], v[28:31]
	v_mfma_f32_16x16x32_bf16 v[40:43], v[136:139], v[218:221], v[40:43]
	v_mfma_f32_16x16x32_bf16 v[60:63], v[100:103], v[222:225], v[60:63]
	v_mfma_f32_16x16x32_bf16 v[48:51], v[104:107], v[222:225], v[48:51]
	v_mfma_f32_16x16x32_bf16 v[36:39], v[108:111], v[222:225], v[36:39]
	v_mfma_f32_16x16x32_bf16 v[28:31], v[112:115], v[222:225], v[28:31]
	v_mfma_f32_16x16x32_bf16 v[40:43], v[136:139], v[222:225], v[40:43]
	s_branch .LBB0_204
